# speedup vs baseline: 1.0166x; 1.0166x over previous
; template <int LOG2N> __device__ __forceinline__ void hyena_item(const Params& p, int j, int ch, int sa, int sb, char* shm_) {
;     ...
;   int sta = seq_start(sa), stb = seq_start(sb);
;   auto conv3 = [&](int part, int st, int t) -> float {
;     const h16* r = PT + (size_t)(part * 512 + ch) * T_TOK + st;
;     int c = part * 512 + ch;
;     float v = cb[c] + cw[1 * 1536 + c] * (float)r[t];
;     if (t > 0) v += cw[0 * 1536 + c] * (float)r[t - 1];
;     if (t < L - 1) v += cw[2 * 1536 + c] * (float)r[t + 1];
;     return v;
;   };
;   f32x2 z[PER], g[PER];
; #pragma unroll
;   for (int u = 0; u < PER; ++u) {
;     int t = TID + NTHREADS * u;
;     z[u] = f32x2{conv3(0, sta, t), conv3(0, stb, t)};
;     g[u] = f32x2{conv3(1, sta, t), conv3(1, stb, t)};
; __device__ __forceinline__ void odd_scan_phase(const Params& p, int layer, char* shm_) {
;     ...
;   for (;;) {
;     if (TID == 0) s_item2 = atomicAdd(ctr, 1);
;     __syncthreads();
;     int it = s_item2;
;     __syncthreads();
;     if (it >= 20 + 512 + 2048) break;
;     if (it < 4) lru_item(p, 8 + (it >> 1), it & 1);
;     else if (it < 20) { int q = it - 4; lru_item(p, q >> 1, q & 1); }
;     else if (it < 532) hyena_item<14>(p, j, it - 20, 8, 9, shm_);
;     else { int q = it - 532; hyena_item<13>(p, j, q & 511, (q >> 9) * 2, (q >> 9) * 2 + 1, shm_); }
.LBB0_360:
	s_or_b64 exec, exec, s[2:3]
	s_waitcnt lgkmcnt(0)
	s_barrier
	ds_read_b32 v0, v1 offset:256
	s_movk_i32 s2, 0xa13
	s_waitcnt lgkmcnt(0)
	s_barrier
	v_cmp_lt_i32_e32 vcc, s2, v0
	v_readfirstlane_b32 s4, v0
	s_mov_b64 s[2:3], -1
	s_cbranch_vccnz .LBB0_355
	v_writelane_b32 v255, s4, 18
	s_cmp_gt_i32 s4, 3
	s_cbranch_scc0 .LBB0_1321
	v_readlane_b32 s2, v255, 18
	s_cmp_gt_u32 s2, 19
	s_mov_b64 s[2:3], -1
	s_cbranch_scc0 .LBB0_1308
	v_readlane_b32 s2, v255, 18
	s_cmpk_gt_u32 s2, 0x213
	s_mov_b64 s[2:3], -1
	s_cbranch_scc0 .LBB0_739
	v_readlane_b32 s2, v255, 18
	s_add_i32 s4, s2, 0xfffffdec
	v_mov_b32_e32 v22, v172
	s_mov_b32 s6, s97
	v_readlane_b32 s8, v254, 5
	s_and_b32 s59, s4, 0x1ff
	s_ashr_i32 s7, s6, 31
	v_readlane_b32 s10, v254, 7
	v_readlane_b32 s11, v254, 8
	s_add_u32 s2, s10, s6
	s_addc_u32 s3, s11, s7
	v_readlane_b32 s9, v254, 6
	s_add_u32 s62, s2, 0x15400000
	s_addc_u32 s63, s3, 0
	s_lshl_b64 s[2:3], s[6:7], 3
	v_readlane_b32 s8, v253, 2
	v_readlane_b32 s9, v253, 3
	s_add_u32 s12, s8, s2
	s_addc_u32 s13, s9, s3
	s_load_dwordx4 s[8:11], s[12:13], 0x158
	v_readlane_b32 s2, v254, 52
	v_readlane_b32 s3, v254, 53
	v_ashrrev_i32_e32 v23, 31, v22
	s_waitcnt lgkmcnt(0)
	s_add_u32 s60, s8, s2
	v_readlane_b32 s2, v254, 51
	s_addc_u32 s61, s9, s2
	v_readlane_b32 s2, v254, 54
	s_add_u32 s2, s10, s2
	s_addc_u32 s3, s11, s3
	s_lshl_b32 s4, s4, 4
	s_and_b32 s16, s4, 0x7fffe000
	s_mul_i32 s4, s59, 0x18000
	s_add_u32 s17, s62, s4
	s_addc_u32 s18, s63, 0
	s_lshl_b32 s64, s16, 1
	s_add_u32 s42, s17, s64
	s_addc_u32 s43, s18, 0
	s_lshl_b32 s65, s59, 2
	s_add_u32 s8, s60, s65
	v_mov_b32_e32 v0, s65
	s_addc_u32 s9, s61, 0
	v_lshl_add_u64 v[2:3], v[22:23], 1, s[42:43]
	v_lshlrev_b32_e32 v30, 4, v22
	v_add_u32_e32 v31, 0x2000, v30
	s_add_u32 s14, s17, s64
	s_addc_u32 s15, s18, 0
	global_load_dwordx4 v[54:57], v30, s[14:15]
	global_load_dwordx4 v[58:61], v31, s[14:15]
	s_add_u32 s14, s14, 0x3000000
	s_addc_u32 s15, s15, 0
	global_load_dwordx4 v[62:65], v30, s[14:15]
	global_load_dwordx4 v[66:69], v31, s[14:15]
	s_add_u32 s14, s14, 0x3000000
	s_addc_u32 s15, s15, 0
	global_load_dwordx4 v[70:73], v30, s[14:15]
	global_load_dwordx4 v[42:45], v31, s[14:15]
	s_waitcnt vmcnt(0)
	global_load_dword v20, v251, s[8:9] offset:2048
	global_load_ushort v4, v[2:3], off
	global_load_dword v21, v0, s[2:3]
	global_load_dword v52, v0, s[2:3] offset:2048
	v_mov_b32_e32 v0, 0x2000
	global_load_dword v53, v0, s[8:9]
	s_add_u32 s4, s8, 0x800
	s_addc_u32 s5, s9, 0
	v_cmp_lt_i32_e64 s[10:11], 0, v22
	s_waitcnt vmcnt(2)
	v_fma_mix_f32 v30, v20, v4, v21 op_sel_hi:[0,1,0]
	s_and_saveexec_b64 s[14:15], s[10:11]
	s_cbranch_execz .LBB0_366
	global_load_dword v0, v1, s[8:9]
	global_load_ushort v4, v[2:3], off offset:-2
	s_waitcnt vmcnt(0)
	v_fma_mix_f32 v30, v0, v4, v30 op_sel_hi:[0,1,0]

; template <int LOG2N> DEV int brev(int v) { return (int)(__brev((unsigned)v) >> (32 - LOG2N)); }
; template <int LOG2N> DEV void spec_mul(f32x2* x, const f32x2* SP) {
;     ...
;   for (int hp = TID; hp < N / 2; hp += NTHREADS) {
;     int pp = hp * 2;
;     int f = brev<LOG2N>(pp);
;     f32x2 k = SP[hp];
.LBB0_534:
	s_or_b64 exec, exec, s[4:5]
	v_mov_b32_e32 v50, v172
	s_movk_i32 s4, 0x1000
	s_lshl_b32 s48, s59, 15
	s_waitcnt lgkmcnt(0)
	s_barrier
	s_nop 0
	v_cmp_gt_i32_e32 vcc, s4, v50
	s_and_saveexec_b64 s[4:5], vcc
	s_cbranch_execz .LBB0_541
	v_readlane_b32 s8, v253, 48
	s_add_u32 s8, s8, s6
	v_readlane_b32 s9, v253, 49
	s_addc_u32 s9, s9, s7
	s_add_u32 s8, s8, s48
	v_ashrrev_i32_e32 v51, 31, v50
	s_addc_u32 s9, s9, 0
	v_add_u32_e32 v25, 0xfffffe00, v50
	v_lshl_add_u64 v[46:47], v[50:51], 3, s[8:9]
	v_lshl_add_u32 v27, v50, 4, v182
	v_lshlrev_b32_e32 v29, 1, v50
	v_lshlrev_b32_e32 v33, 3, v50
	global_load_dwordx2 v[50:51], v33, s[8:9]
	v_add_u32_e32 v33, 0x1000, v33
	global_load_dwordx2 v[50:51], v33, s[8:9]
	v_add_u32_e32 v33, 0x1000, v33
	global_load_dwordx2 v[50:51], v33, s[8:9]
	v_add_u32_e32 v33, 0x1000, v33
	global_load_dwordx2 v[50:51], v33, s[8:9]
	v_add_u32_e32 v33, 0x1000, v33
	global_load_dwordx2 v[50:51], v33, s[8:9]
	v_add_u32_e32 v33, 0x1000, v33
	global_load_dwordx2 v[50:51], v33, s[8:9]
	v_add_u32_e32 v33, 0x1000, v33
	global_load_dwordx2 v[50:51], v33, s[8:9]
	v_add_u32_e32 v33, 0x1000, v33
	global_load_dwordx2 v[50:51], v33, s[8:9]
	s_waitcnt vmcnt(0)
	s_mov_b64 s[8:9], 0
	s_branch .LBB0_537

; template <int LOG2N> DEV int brev(int v) { return (int)(__brev((unsigned)v) >> (32 - LOG2N)); }
; template <int LOG2N> DEV void spec_mul(f32x2* x, const f32x2* SP) {
;     ...
;   for (int hp = TID; hp < N / 2; hp += NTHREADS) {
;     int pp = hp * 2;
;     int f = brev<LOG2N>(pp);
;     f32x2 k = SP[hp];
.LBB0_689:
	s_or_b64 exec, exec, s[2:3]
	v_mov_b32_e32 v58, v172
	s_movk_i32 s2, 0x1000
	s_waitcnt lgkmcnt(0)
	s_barrier
	s_nop 0
	v_cmp_gt_i32_e32 vcc, s2, v58
	s_and_saveexec_b64 s[2:3], vcc
	s_cbranch_execz .LBB0_696
	v_readlane_b32 s4, v253, 57
	s_add_u32 s4, s4, s6
	v_readlane_b32 s5, v253, 58
	s_addc_u32 s5, s5, s7
	s_add_u32 s4, s4, s48
	v_ashrrev_i32_e32 v59, 31, v58
	s_addc_u32 s5, s5, 0
	v_add_u32_e32 v47, 0xfffffe00, v58
	v_lshl_add_u64 v[40:41], v[58:59], 3, s[4:5]
	v_lshl_add_u32 v59, v58, 4, v182
	v_lshlrev_b32_e32 v60, 1, v58
	v_lshlrev_b32_e32 v61, 3, v58
	global_load_dwordx2 v[62:63], v61, s[4:5]
	v_add_u32_e32 v61, 0x1000, v61
	global_load_dwordx2 v[62:63], v61, s[4:5]
	v_add_u32_e32 v61, 0x1000, v61
	global_load_dwordx2 v[62:63], v61, s[4:5]
	v_add_u32_e32 v61, 0x1000, v61
	global_load_dwordx2 v[62:63], v61, s[4:5]
	v_add_u32_e32 v61, 0x1000, v61
	global_load_dwordx2 v[62:63], v61, s[4:5]
	v_add_u32_e32 v61, 0x1000, v61
	global_load_dwordx2 v[62:63], v61, s[4:5]
	v_add_u32_e32 v61, 0x1000, v61
	global_load_dwordx2 v[62:63], v61, s[4:5]
	v_add_u32_e32 v61, 0x1000, v61
	global_load_dwordx2 v[62:63], v61, s[4:5]
	s_waitcnt vmcnt(0)
	s_mov_b64 s[4:5], 0
	s_branch .LBB0_692

; template <int LOG2N> __device__ __forceinline__ void hyena_item(const Params& p, int j, int ch, int sa, int sb, char* shm_) {
;     ...
;   int sta = seq_start(sa), stb = seq_start(sb);
;   auto conv3 = [&](int part, int st, int t) -> float {
;     const h16* r = PT + (size_t)(part * 512 + ch) * T_TOK + st;
;     int c = part * 512 + ch;
;     float v = cb[c] + cw[1 * 1536 + c] * (float)r[t];
;     if (t > 0) v += cw[0 * 1536 + c] * (float)r[t - 1];
;     if (t < L - 1) v += cw[2 * 1536 + c] * (float)r[t + 1];
;     return v;
;   };
;   f32x2 z[PER], g[PER];
; #pragma unroll
;   for (int u = 0; u < PER; ++u) {
;     int t = TID + NTHREADS * u;
;     z[u] = f32x2{conv3(0, sta, t), conv3(0, stb, t)};
;     g[u] = f32x2{conv3(1, sta, t), conv3(1, stb, t)};
.LBB0_739:
	s_and_b64 vcc, exec, s[2:3]
	s_cbranch_vccz .LBB0_1307
	v_readlane_b32 s2, v255, 18
	v_mov_b32_e32 v54, v172
	s_mov_b32 s8, s97
	v_readlane_b32 s4, v254, 5
	s_sub_i32 s96, s2, 20
	s_ashr_i32 s9, s8, 31
	v_readlane_b32 s6, v254, 7
	v_readlane_b32 s7, v254, 8
	s_add_u32 s2, s6, s8
	s_addc_u32 s3, s7, s9
	v_readlane_b32 s5, v254, 6
	s_add_u32 s12, s2, 0x15400000
	s_addc_u32 s16, s3, 0
	v_writelane_b32 v255, s8, 19
	s_lshl_b64 s[2:3], s[8:9], 3
	v_readlane_b32 s4, v253, 2
	v_readlane_b32 s5, v253, 3
	s_add_u32 s4, s4, s2
	s_addc_u32 s5, s5, s3
	v_writelane_b32 v255, s9, 20
	s_load_dwordx4 s[8:11], s[4:5], 0x158
	v_readlane_b32 s2, v254, 52
	s_mul_i32 s3, s96, 0x18000
	v_writelane_b32 v255, s12, 21
	v_ashrrev_i32_e32 v55, 31, v54
	s_waitcnt lgkmcnt(0)
	s_add_u32 s6, s8, s2
	v_readlane_b32 s2, v254, 51
	s_addc_u32 s7, s9, s2
	v_readlane_b32 s2, v254, 54
	s_add_u32 s8, s10, s2
	v_readlane_b32 s2, v254, 53
	s_addc_u32 s9, s11, s2
	s_mul_hi_u32 s2, s96, 0x18000
	s_add_u32 s14, s12, s3
	s_addc_u32 s15, s16, s2
	s_add_u32 s74, s14, 0x10000
	s_addc_u32 s75, s15, 0
	s_lshl_b64 s[2:3], s[96:97], 2
	v_writelane_b32 v255, s8, 22
	s_add_u32 s8, s8, s2
	v_writelane_b32 v255, s9, 23
	s_addc_u32 s9, s9, s3
	s_add_u32 s90, s6, s2
	s_addc_u32 s91, s7, s3
	v_lshlrev_b32_e32 v70, 4, v54
	v_add_u32_e32 v71, 0x2000, v70
	v_add_u32_e32 v74, 0x4000, v70
	v_add_u32_e32 v75, 0x6000, v70
	s_mov_b32 s76, s74
	s_mov_b32 s77, s75
	global_load_dwordx4 v[120:123], v70, s[76:77]
	global_load_dwordx4 v[124:127], v71, s[76:77]
	global_load_dwordx4 v[128:131], v74, s[76:77]
	global_load_dwordx4 v[132:135], v75, s[76:77]
	s_add_u32 s76, s76, 0x3000000
	s_addc_u32 s77, s77, 0
	global_load_dwordx4 v[136:139], v70, s[76:77]
	global_load_dwordx4 v[140:143], v71, s[76:77]
	global_load_dwordx4 v[144:147], v74, s[76:77]
	global_load_dwordx4 v[148:151], v75, s[76:77]
	s_add_u32 s76, s76, 0x3000000
	s_addc_u32 s77, s77, 0
	global_load_dwordx4 v[152:155], v70, s[76:77]
	global_load_dwordx4 v[156:159], v71, s[76:77]
	global_load_dwordx4 v[78:81], v74, s[76:77]
	global_load_dwordx4 v[88:91], v75, s[76:77]
	s_waitcnt vmcnt(0)
	global_load_dword v52, v251, s[90:91] offset:2048
	v_lshl_add_u64 v[2:3], v[54:55], 1, s[74:75]
	v_mov_b32_e32 v4, 0x2000
	global_load_ushort v0, v[2:3], off
	global_load_dword v53, v1, s[8:9]
	global_load_dword v112, v1, s[8:9] offset:2048
	global_load_dword v113, v4, s[90:91]
	v_writelane_b32 v255, s6, 24
	s_add_u32 s76, s90, 0x800
	v_writelane_b32 v255, s7, 25
	s_addc_u32 s77, s91, 0
	v_cmp_lt_i32_e64 s[10:11], 0, v54
	s_waitcnt vmcnt(2)
	v_fma_mix_f32 v70, v52, v0, v53 op_sel_hi:[0,1,0]
	s_and_saveexec_b64 s[8:9], s[10:11]
	s_cbranch_execz .LBB0_742
	global_load_dword v0, v1, s[90:91]
	global_load_ushort v4, v[2:3], off offset:-2
	s_waitcnt vmcnt(0)
	v_fma_mix_f32 v70, v0, v4, v70 op_sel_hi:[0,1,0]

; template <int LOG2N> DEV int brev(int v) { return (int)(__brev((unsigned)v) >> (32 - LOG2N)); }
; template <int LOG2N> DEV void spec_mul(f32x2* x, const f32x2* SP) {
;     ...
;   for (int hp = TID; hp < N / 2; hp += NTHREADS) {
;     int pp = hp * 2;
;     int f = brev<LOG2N>(pp);
;     f32x2 k = SP[hp];
.LBB0_1038:
	s_or_b64 exec, exec, s[4:5]
	v_mov_b32_e32 v110, v172
	s_movk_i32 s4, 0x2000
	s_waitcnt lgkmcnt(0)
	s_barrier
	s_nop 0
	v_cmp_gt_i32_e32 vcc, s4, v110
	s_and_saveexec_b64 s[4:5], vcc
	s_cbranch_execz .LBB0_1045
	s_lshl_b64 s[6:7], s[96:97], 16
	v_readlane_b32 s8, v253, 51
	v_readlane_b32 s76, v255, 19
	v_readlane_b32 s77, v255, 20
	s_add_u32 s8, s8, s76
	v_readlane_b32 s9, v253, 52
	s_addc_u32 s9, s9, s77
	s_add_u32 s6, s8, s6
	v_ashrrev_i32_e32 v111, 31, v110
	s_addc_u32 s7, s9, s7
	v_add_u32_e32 v113, 0xfffffe00, v110
	v_lshl_add_u64 v[104:105], v[110:111], 3, s[6:7]
	v_lshl_add_u32 v111, v110, 4, v182
	v_lshlrev_b32_e32 v114, 1, v110
	v_lshlrev_b32_e32 v115, 3, v110
	global_load_dwordx2 v[116:117], v115, s[6:7]
	v_add_u32_e32 v115, 0x1000, v115
	global_load_dwordx2 v[116:117], v115, s[6:7]
	v_add_u32_e32 v115, 0x1000, v115
	global_load_dwordx2 v[116:117], v115, s[6:7]
	v_add_u32_e32 v115, 0x1000, v115
	global_load_dwordx2 v[116:117], v115, s[6:7]
	v_add_u32_e32 v115, 0x1000, v115
	global_load_dwordx2 v[116:117], v115, s[6:7]
	v_add_u32_e32 v115, 0x1000, v115
	global_load_dwordx2 v[116:117], v115, s[6:7]
	v_add_u32_e32 v115, 0x1000, v115
	global_load_dwordx2 v[116:117], v115, s[6:7]
	v_add_u32_e32 v115, 0x1000, v115
	global_load_dwordx2 v[116:117], v115, s[6:7]
	v_add_u32_e32 v115, 0x1000, v115
	global_load_dwordx2 v[116:117], v115, s[6:7]
	v_add_u32_e32 v115, 0x1000, v115
	global_load_dwordx2 v[116:117], v115, s[6:7]
	v_add_u32_e32 v115, 0x1000, v115
	global_load_dwordx2 v[116:117], v115, s[6:7]
	v_add_u32_e32 v115, 0x1000, v115
	global_load_dwordx2 v[116:117], v115, s[6:7]
	v_add_u32_e32 v115, 0x1000, v115
	global_load_dwordx2 v[116:117], v115, s[6:7]
	v_add_u32_e32 v115, 0x1000, v115
	global_load_dwordx2 v[116:117], v115, s[6:7]
	v_add_u32_e32 v115, 0x1000, v115
	global_load_dwordx2 v[116:117], v115, s[6:7]
	v_add_u32_e32 v115, 0x1000, v115
	global_load_dwordx2 v[116:117], v115, s[6:7]
	s_waitcnt vmcnt(0)
	s_mov_b64 s[8:9], 0
	s_branch .LBB0_1041

; template <int LOG2N> DEV int brev(int v) { return (int)(__brev((unsigned)v) >> (32 - LOG2N)); }
; template <int LOG2N> DEV void spec_mul(f32x2* x, const f32x2* SP) {
;     ...
;   for (int hp = TID; hp < N / 2; hp += NTHREADS) {
;     int pp = hp * 2;
;     int f = brev<LOG2N>(pp);
;     f32x2 k = SP[hp];
.LBB0_1257:
	s_or_b64 exec, exec, s[2:3]
	v_mov_b32_e32 v122, v172
	s_movk_i32 s2, 0x2000
	s_waitcnt lgkmcnt(0)
	s_barrier
	s_nop 0
	v_cmp_gt_i32_e32 vcc, s2, v122
	s_and_saveexec_b64 s[2:3], vcc
	s_cbranch_execz .LBB0_1264
	v_readlane_b32 s4, v255, 18
	s_add_i32 s96, s4, 0x1ec
	s_lshl_b64 s[4:5], s[96:97], 16
	v_readlane_b32 s6, v253, 51
	v_readlane_b32 s8, v255, 19
	v_readlane_b32 s9, v255, 20
	s_add_u32 s6, s6, s8
	v_readlane_b32 s7, v253, 52
	s_addc_u32 s7, s7, s9
	s_add_u32 s4, s6, s4
	v_ashrrev_i32_e32 v123, 31, v122
	s_addc_u32 s5, s7, s5
	v_add_u32_e32 v105, 0xfffffe00, v122
	v_lshl_add_u64 v[100:101], v[122:123], 3, s[4:5]
	v_lshl_add_u32 v123, v122, 4, v182
	v_lshlrev_b32_e32 v124, 1, v122
	v_lshlrev_b32_e32 v125, 3, v122
	global_load_dwordx2 v[126:127], v125, s[4:5]
	v_add_u32_e32 v125, 0x1000, v125
	global_load_dwordx2 v[126:127], v125, s[4:5]
	v_add_u32_e32 v125, 0x1000, v125
	global_load_dwordx2 v[126:127], v125, s[4:5]
	v_add_u32_e32 v125, 0x1000, v125
	global_load_dwordx2 v[126:127], v125, s[4:5]
	v_add_u32_e32 v125, 0x1000, v125
	global_load_dwordx2 v[126:127], v125, s[4:5]
	v_add_u32_e32 v125, 0x1000, v125
	global_load_dwordx2 v[126:127], v125, s[4:5]
	v_add_u32_e32 v125, 0x1000, v125
	global_load_dwordx2 v[126:127], v125, s[4:5]
	v_add_u32_e32 v125, 0x1000, v125
	global_load_dwordx2 v[126:127], v125, s[4:5]
	v_add_u32_e32 v125, 0x1000, v125
	global_load_dwordx2 v[126:127], v125, s[4:5]
	v_add_u32_e32 v125, 0x1000, v125
	global_load_dwordx2 v[126:127], v125, s[4:5]
	v_add_u32_e32 v125, 0x1000, v125
	global_load_dwordx2 v[126:127], v125, s[4:5]
	v_add_u32_e32 v125, 0x1000, v125
	global_load_dwordx2 v[126:127], v125, s[4:5]
	v_add_u32_e32 v125, 0x1000, v125
	global_load_dwordx2 v[126:127], v125, s[4:5]
	v_add_u32_e32 v125, 0x1000, v125
	global_load_dwordx2 v[126:127], v125, s[4:5]
	v_add_u32_e32 v125, 0x1000, v125
	global_load_dwordx2 v[126:127], v125, s[4:5]
	v_add_u32_e32 v125, 0x1000, v125
	global_load_dwordx2 v[126:127], v125, s[4:5]
	s_waitcnt vmcnt(0)
	s_mov_b64 s[4:5], 0
	s_branch .LBB0_1260
